# YB and down-proj residual GEMM epilogues: side-operand loads issued many chunks ahead into dead fragment registers, exact counted waits
# speedup vs baseline: 1.0101x; 1.0075x over previous
; #define SLOAD() do { vs0 = *(const bf16x8*)(Vh + voff); vs1 = *(const bf16x8*)(Vh + voff + 32u * (unsigned)ldv); \
;     ks0 = *(const bf16x8*)(Kh + koff); ks1 = *(const bf16x8*)(Kh + koff + 32u * (unsigned)ldk); \
;     if constexpr (NR > 0) { kr = *(const bf16x8*)(Krh + kroff); kroff += 64u * 64u; } voff += 64u * (unsigned)ldv; koff += 64u * (unsigned)ldk; } while (0)
; #define SWRITE(b) do { *(bf16x8*)(V_lds + (b) * SHM_V + vst0) = vs0; *(bf16x8*)(V_lds + (b) * SHM_V + vst1) = vs1; const int kc = sc * 2;  \
;     *(bf16x8*)(K_lds + (b) * SHM_K + KSWZ(sr, kc)) = ks0; *(bf16x8*)(K_lds + (b) * SHM_K + KSWZ(32 + sr, kc)) = ks1; \
;     if constexpr (NR > 0) *(bf16x8*)(Kr_lds + (b) * SHM_KR + krst) = kr; } while (0)
; #define SLOAD() do { vs0 = *(const bf16x8*)(Vh + voff); vs1 = *(const bf16x8*)(Vh + voff + 32u * (unsigned)ldv); \
;     ks0 = *(const bf16x8*)(Kh + voff); ks1 = *(const bf16x8*)(Kh + voff + 32u * (unsigned)ldv); \
;     if constexpr (NR > 0) { kr = *(const bf16x8*)(Krh + kroff); kroff += 64u * 64u; } voff += 64u * (unsigned)ldv; } while (0)
; #define SWRITE(b) do { *(bf16x8*)(V_lds + (b) * SHM_V + vst0) = vs0; *(bf16x8*)(V_lds + (b) * SHM_V + vst0 + 8192) = vs1;  \
;     *(bf16x8*)(K_lds + (b) * SHM_K + kst0) = ks0; *(bf16x8*)(K_lds + (b) * SHM_K + kst0 + 8192) = ks1; \
;     if constexpr (NR > 0) *(bf16x8*)(Kr_lds + (b) * SHM_KR + krst) = kr; } while (0)
; #define RESC(a) do { if (__any((a) < 1.f)) { if (hi == 0) al_l[r32] = (a); asm volatile("s_waitcnt lgkmcnt(0)" ::: "memory"); \
;     _Pragma("unroll") for (int d = 0; d < 4; ++d) _Pragma("unroll") for (int r = 0; r < 16; ++r) o[d][r] *= al_l[crow(r, hi)]; } } while (0)
; #define SLOAD() do { vs0 = *(const bf16x8*)(Vh + voff); vs1 = *(const bf16x8*)(Vh + voff + 32u * (unsigned)ldv); kn = *(const v4i32*)(Kn8 + knoff); \
;     if (krw) kr = *(const v4i32*)(Kr8 + kroff); voff += 64u * (unsigned)ldv; knoff += 64u * (unsigned)ldk; kroff += 64u * 64u; } while (0)
; __device__ __forceinline__ void attn_unit7(const unsigned char* __restrict__ Q8, int ldq, const unsigned char* __restrict__ Kn8, int ldk, const unsigned char* __restrict__ Kr8, ...
;     ...
;     __syncthreads(); SWRITE(0);
;     RESC(alB); __syncthreads();
;     if (j + 2 < NT) SLOAD();
.Lmla_A_cont:
	s_barrier
	s_waitcnt vmcnt(0)
	ds_write_b128 v210, v[158:161]
	ds_write_b128 v211, v[162:165] offset:16384
	s_and_saveexec_b64 s[20:21], s[42:43]
	ds_write_b128 v212, v[154:157] offset:32768
	s_or_b64 exec, exec, s[20:21]
	s_waitcnt lgkmcnt(0)
	s_barrier
	global_load_dwordx4 v[158:161], v176, s[18:19]
	global_load_dwordx4 v[162:165], v178, s[16:17]
	s_and_saveexec_b64 s[20:21], s[42:43]
	s_cbranch_execz .Lmla_B_nokr
	global_load_dwordx4 v[154:157], v[180:181], off

; __device__ __forceinline__ void partialSM9(f32x16& p0, f32x16& p1, float& m_run, float& alpha, const float thr2) {
;   float pmax = p0[0];
; #pragma unroll
;   for (int r = 1; r < 16; ++r) pmax = fmaxf(pmax, p0[r]);
; #pragma unroll
;   for (int r = 0; r < 16; ++r) pmax = fmaxf(pmax, p1[r]);
;   { auto rr = __builtin_amdgcn_permlane32_swap(__float_as_uint(pmax), __float_as_uint(pmax), false, false);
;     pmax = fmaxf(__uint_as_float(rr[0]), __uint_as_float(rr[1])); }
;   if (__builtin_expect(__all(pmax <= 7.0f + thr2), 1)) { alpha = 1.f; }
;   else { const float delta = fmaxf(pmax - 7.0f, 0.f); alpha = __builtin_amdgcn_exp2f(-delta); m_run += delta;
; #pragma unroll
;     for (int r = 0; r < 16; ++r) { p0[r] -= delta; p1[r] -= delta; } }
.Lmla_B_cont:
	s_barrier
	s_waitcnt vmcnt(0)
	ds_write_b128 v210, v[158:161] offset:8192
	ds_write_b128 v211, v[162:165] offset:24576
	s_and_saveexec_b64 s[20:21], s[42:43]
	ds_write_b128 v212, v[154:157] offset:36864
	s_or_b64 exec, exec, s[20:21]
	s_add_i32 s30, s30, 2
	v_mov_b32_e32 v0, v218
	s_waitcnt lgkmcnt(0)
	s_barrier
	s_cmpk_gt_u32 s30, 0xfc
	s_cbranch_scc0 .LBB0_1321
	s_branch .LBB0_1343
.Lmla_A_newmax:
	v_add_f32_e32 v0, 0xc0e00000, v177
	v_max_f32_e32 v177, 0, v0
	v_exp_f32_e64 v221, -v177
	v_add_f32_e32 v217, v217, v177
	v_sub_f32_e32 v129, v129, v177
	v_sub_f32_e32 v128, v128, v177
	v_sub_f32_e32 v127, v127, v177
	v_sub_f32_e32 v126, v126, v177
	v_sub_f32_e32 v125, v125, v177
	v_sub_f32_e32 v124, v124, v177
	v_sub_f32_e32 v123, v123, v177
	v_sub_f32_e32 v122, v122, v177
	v_sub_f32_e32 v121, v121, v177
	v_sub_f32_e32 v120, v120, v177
	v_sub_f32_e32 v119, v119, v177
	v_sub_f32_e32 v118, v118, v177
	v_sub_f32_e32 v117, v117, v177
	v_sub_f32_e32 v116, v116, v177
	v_sub_f32_e32 v115, v115, v177
	v_sub_f32_e32 v114, v114, v177
	s_and_saveexec_b64 s[20:21], s[40:41]
	ds_write_b32 v208, v221 offset:41088
	s_or_b64 exec, exec, s[20:21]
	v_sub_f32_e32 v113, v113, v177
	v_sub_f32_e32 v112, v112, v177
	v_sub_f32_e32 v111, v111, v177
	v_sub_f32_e32 v110, v110, v177
	v_sub_f32_e32 v109, v109, v177
	v_sub_f32_e32 v108, v108, v177
	v_sub_f32_e32 v107, v107, v177
	v_sub_f32_e32 v106, v106, v177
	v_sub_f32_e32 v105, v105, v177
	v_sub_f32_e32 v104, v104, v177
	v_sub_f32_e32 v103, v103, v177
	v_sub_f32_e32 v102, v102, v177
	v_sub_f32_e32 v101, v101, v177
	v_sub_f32_e32 v100, v100, v177
	v_sub_f32_e32 v99, v99, v177
	v_sub_f32_e32 v98, v98, v177
	v_sub_f32_e32 v230, 0x40e00000, v217
	v_mov_b32_e32 v231, v230
	v_mov_b32_e32 v232, v230
	v_mov_b32_e32 v233, v230
	v_mov_b32_e32 v234, v230
	v_mov_b32_e32 v235, v230
	v_mov_b32_e32 v236, v230
	v_mov_b32_e32 v237, v230
	v_mov_b32_e32 v238, v230
	v_mov_b32_e32 v239, v230
	v_mov_b32_e32 v240, v230
	v_mov_b32_e32 v241, v230
	v_mov_b32_e32 v242, v230
	v_mov_b32_e32 v243, v230
	v_mov_b32_e32 v244, v230
	v_mov_b32_e32 v245, v230
	v_add_u32_e32 v0, v187, v207
	s_waitcnt lgkmcnt(0)
	ds_read_b128 v[66:69], v0 offset:41184
	ds_read_b128 v[70:73], v0 offset:41152
	ds_read_b128 v[74:77], v0 offset:41120
	ds_read_b128 v[78:81], v0 offset:41088
	s_waitcnt lgkmcnt(0)
	v_pk_mul_f32 v[62:63], v[62:63], v[66:67]
	v_pk_mul_f32 v[58:59], v[58:59], v[70:71]
	v_pk_mul_f32 v[54:55], v[54:55], v[74:75]
	v_pk_mul_f32 v[64:65], v[64:65], v[68:69]
	v_pk_mul_f32 v[60:61], v[60:61], v[72:73]
	v_pk_mul_f32 v[56:57], v[56:57], v[76:77]
	v_pk_mul_f32 v[52:53], v[52:53], v[80:81]
	v_pk_mul_f32 v[50:51], v[50:51], v[78:79]
	v_pk_mul_f32 v[46:47], v[46:47], v[66:67]
	v_pk_mul_f32 v[42:43], v[42:43], v[70:71]
	v_pk_mul_f32 v[38:39], v[38:39], v[74:75]
	v_pk_mul_f32 v[48:49], v[48:49], v[68:69]
	v_pk_mul_f32 v[44:45], v[44:45], v[72:73]
	v_pk_mul_f32 v[40:41], v[40:41], v[76:77]
	v_pk_mul_f32 v[36:37], v[36:37], v[80:81]
	v_pk_mul_f32 v[34:35], v[34:35], v[78:79]
	v_pk_mul_f32 v[30:31], v[30:31], v[66:67]
	v_pk_mul_f32 v[26:27], v[26:27], v[70:71]
	v_pk_mul_f32 v[22:23], v[22:23], v[74:75]
	v_pk_mul_f32 v[32:33], v[32:33], v[68:69]
	v_pk_mul_f32 v[28:29], v[28:29], v[72:73]
	v_pk_mul_f32 v[24:25], v[24:25], v[76:77]
	v_pk_mul_f32 v[20:21], v[20:21], v[80:81]
	v_pk_mul_f32 v[18:19], v[18:19], v[78:79]
	v_pk_mul_f32 v[14:15], v[14:15], v[66:67]
	v_pk_mul_f32 v[10:11], v[10:11], v[70:71]
	v_pk_mul_f32 v[6:7], v[6:7], v[74:75]
	v_pk_mul_f32 v[16:17], v[16:17], v[68:69]
	v_pk_mul_f32 v[12:13], v[12:13], v[72:73]
	v_pk_mul_f32 v[8:9], v[8:9], v[76:77]
	v_pk_mul_f32 v[4:5], v[4:5], v[80:81]
	v_pk_mul_f32 v[2:3], v[2:3], v[78:79]
	s_branch .Lmla_A_cont
.Lmla_B_newmax:
	v_add_f32_e32 v0, 0xc0e00000, v177
	v_max_f32_e32 v177, 0, v0
	v_exp_f32_e64 v218, -v177
	v_add_f32_e32 v217, v217, v177
	v_sub_f32_e32 v97, v97, v177
	v_sub_f32_e32 v96, v96, v177
	v_sub_f32_e32 v95, v95, v177
	v_sub_f32_e32 v94, v94, v177
	v_sub_f32_e32 v93, v93, v177
	v_sub_f32_e32 v92, v92, v177
	v_sub_f32_e32 v91, v91, v177
	v_sub_f32_e32 v90, v90, v177
	v_sub_f32_e32 v89, v89, v177
	v_sub_f32_e32 v88, v88, v177
	v_sub_f32_e32 v87, v87, v177
	v_sub_f32_e32 v86, v86, v177
	v_sub_f32_e32 v85, v85, v177
	v_sub_f32_e32 v84, v84, v177
	v_sub_f32_e32 v83, v83, v177
	v_sub_f32_e32 v82, v82, v177
	s_and_saveexec_b64 s[20:21], s[40:41]
	ds_write_b32 v208, v218 offset:41088
	s_or_b64 exec, exec, s[20:21]
	v_sub_f32_e32 v81, v81, v177
	v_sub_f32_e32 v80, v80, v177
	v_sub_f32_e32 v79, v79, v177
	v_sub_f32_e32 v78, v78, v177
	v_sub_f32_e32 v77, v77, v177
	v_sub_f32_e32 v76, v76, v177
	v_sub_f32_e32 v75, v75, v177
	v_sub_f32_e32 v74, v74, v177
	v_sub_f32_e32 v73, v73, v177
	v_sub_f32_e32 v72, v72, v177
	v_sub_f32_e32 v71, v71, v177
	v_sub_f32_e32 v70, v70, v177
	v_sub_f32_e32 v69, v69, v177
	v_sub_f32_e32 v68, v68, v177
	v_sub_f32_e32 v67, v67, v177
	v_sub_f32_e32 v66, v66, v177
	v_sub_f32_e32 v230, 0x40e00000, v217
	v_mov_b32_e32 v231, v230
	v_mov_b32_e32 v232, v230
	v_mov_b32_e32 v233, v230
	v_mov_b32_e32 v234, v230
	v_mov_b32_e32 v235, v230
	v_mov_b32_e32 v236, v230
	v_mov_b32_e32 v237, v230
	v_mov_b32_e32 v238, v230
	v_mov_b32_e32 v239, v230
	v_mov_b32_e32 v240, v230
	v_mov_b32_e32 v241, v230
	v_mov_b32_e32 v242, v230
	v_mov_b32_e32 v243, v230
	v_mov_b32_e32 v244, v230
	v_mov_b32_e32 v245, v230
	v_add_u32_e32 v0, v187, v207
	s_waitcnt lgkmcnt(0)
	ds_read_b128 v[98:101], v0 offset:41184
	ds_read_b128 v[102:105], v0 offset:41152
	ds_read_b128 v[106:109], v0 offset:41120
	ds_read_b128 v[110:113], v0 offset:41088
	s_waitcnt lgkmcnt(0)
	v_pk_mul_f32 v[62:63], v[62:63], v[98:99]
	v_pk_mul_f32 v[58:59], v[58:59], v[102:103]
	v_pk_mul_f32 v[54:55], v[54:55], v[106:107]
	v_pk_mul_f32 v[64:65], v[64:65], v[100:101]
	v_pk_mul_f32 v[60:61], v[60:61], v[104:105]
	v_pk_mul_f32 v[56:57], v[56:57], v[108:109]
	v_pk_mul_f32 v[52:53], v[52:53], v[112:113]
	v_pk_mul_f32 v[50:51], v[50:51], v[110:111]
	v_pk_mul_f32 v[46:47], v[46:47], v[98:99]
	v_pk_mul_f32 v[42:43], v[42:43], v[102:103]
	v_pk_mul_f32 v[38:39], v[38:39], v[106:107]
	v_pk_mul_f32 v[48:49], v[48:49], v[100:101]
	v_pk_mul_f32 v[44:45], v[44:45], v[104:105]
	v_pk_mul_f32 v[40:41], v[40:41], v[108:109]
	v_pk_mul_f32 v[36:37], v[36:37], v[112:113]
	v_pk_mul_f32 v[34:35], v[34:35], v[110:111]
	v_pk_mul_f32 v[30:31], v[30:31], v[98:99]
	v_pk_mul_f32 v[26:27], v[26:27], v[102:103]
	v_pk_mul_f32 v[22:23], v[22:23], v[106:107]
	v_pk_mul_f32 v[32:33], v[32:33], v[100:101]
	v_pk_mul_f32 v[28:29], v[28:29], v[104:105]
	v_pk_mul_f32 v[24:25], v[24:25], v[108:109]
	v_pk_mul_f32 v[20:21], v[20:21], v[112:113]
	v_pk_mul_f32 v[18:19], v[18:19], v[110:111]
	v_pk_mul_f32 v[14:15], v[14:15], v[98:99]
	v_pk_mul_f32 v[10:11], v[10:11], v[102:103]
	v_pk_mul_f32 v[6:7], v[6:7], v[106:107]
	v_pk_mul_f32 v[16:17], v[16:17], v[100:101]
	v_pk_mul_f32 v[12:13], v[12:13], v[104:105]
	v_pk_mul_f32 v[8:9], v[8:9], v[108:109]
	v_pk_mul_f32 v[4:5], v[4:5], v[112:113]
	v_pk_mul_f32 v[2:3], v[2:3], v[110:111]
	s_branch .Lmla_B_cont

; #define EGAS __attribute__((address_space(1)))
; __device__ __forceinline__ void ld8f8(const EGAS unsigned char* src, f32x4& v0, f32x4& v1) {
;     typedef float f32x2g __attribute__((ext_vector_type(2)));
;     const u32x2e w = *(const EGAS u32x2e*)src;
;     const f32x2g a = __builtin_amdgcn_cvt_pk_f32_fp8((int)w.x, false), b = __builtin_amdgcn_cvt_pk_f32_fp8((int)w.x, true), c = __builtin_amdgcn_cvt_pk_f32_fp8((int)w.y, false), d = __builtin_amdgcn_cvt_pk_f32_fp8((int)w.y, true);
;     v0 = (f32x4){a.x, a.y, b.x, b.y}; v1 = (f32x4){c.x, c.y, d.x, d.y}; }
; __device__ __forceinline__ void ld8(const EGAS bf16_t* src, f32x4& v0, f32x4& v1) {
;     const u32x4 w = *(const EGAS u32x4*)src;
;     v0[0] = __uint_as_float(w.x << 16); v0[1] = __uint_as_float(w.x & 0xffff0000u); v0[2] = __uint_as_float(w.y << 16); v0[3] = __uint_as_float(w.y & 0xffff0000u);
;     v1[0] = __uint_as_float(w.z << 16); v1[1] = __uint_as_float(w.z & 0xffff0000u); v1[2] = __uint_as_float(w.w << 16); v1[3] = __uint_as_float(w.w & 0xffff0000u); }
;     __device__ __forceinline__ void operator()(const f32x4 (&acc)[2][2][4][2], const Unit& u, int wr, int wc, int fr, int fq) const {
;     ...
;                     } else if constexpr (MODE == EP_YB) {
;                         const int c = pn * 256 + ct; f32x4 g0, g1, t0, t1; ld8f8(WS8(WS_GATES) + row * 4096 + 2048 + c, g0, g1); ld8(WSB(WS_T) + row * 2048 + c, t0, t1);
;                         st8(WSB(WS_MERGED) + row * 2048 + c, t0 + v0 * g0, t1 + v1 * g1);
.LBB0_1453:
	v_lshl_add_u32 v150, s26, 8, v146
	v_lshl_or_b32 v144, s27, 8, v148
	v_lshlrev_b32_e32 v0, 12, v150
	v_lshl_add_u64 v[152:153], s[12:13], 0, v[0:1]
	v_ashrrev_i32_e32 v145, 31, v144
	v_lshlrev_b32_e32 v142, 11, v150
	v_mov_b32_e32 v143, v1
	v_lshl_add_u64 v[156:157], v[152:153], 0, v[144:145]
	v_lshlrev_b64 v[160:161], 1, v[142:143]
	v_lshl_add_u64 v[152:153], s[14:15], 0, v[160:161]
	v_lshlrev_b64 v[142:143], 1, v[144:145]
	v_lshl_add_u64 v[162:163], v[152:153], 0, v[142:143]
	v_lshl_add_u32 v152, v150, 12, v144
	global_load_dwordx2 v[208:209], v152, s[12:13] offset:2048
	global_load_dwordx2 v[210:211], v152, s[12:13] offset:2176
	v_add_u32_e32 v153, 0x10000, v152
	global_load_dwordx2 v[212:213], v153, s[12:13] offset:2048
	global_load_dwordx2 v[214:215], v153, s[12:13] offset:2176
	v_add_u32_e32 v153, 0x20000, v152
	global_load_dwordx2 v[216:217], v153, s[12:13] offset:2048
	global_load_dwordx2 v[218:219], v153, s[12:13] offset:2176
	v_add_u32_e32 v153, 0x30000, v152
	global_load_dwordx2 v[220:221], v153, s[12:13] offset:2048
	global_load_dwordx2 v[222:223], v153, s[12:13] offset:2176
	v_add_u32_e32 v153, 0x80000, v152
	global_load_dwordx2 v[224:225], v153, s[12:13] offset:2048
	global_load_dwordx2 v[226:227], v153, s[12:13] offset:2176
	v_add_u32_e32 v153, 0x90000, v152
	global_load_dwordx2 v[228:229], v153, s[12:13] offset:2048
	global_load_dwordx2 v[230:231], v153, s[12:13] offset:2176
	v_add_u32_e32 v153, 0xa0000, v152
	global_load_dwordx2 v[232:233], v153, s[12:13] offset:2048
	global_load_dwordx2 v[234:235], v153, s[12:13] offset:2176
	v_add_u32_e32 v153, 0xb0000, v152
	global_load_dwordx2 v[236:237], v153, s[12:13] offset:2048
	global_load_dwordx2 v[238:239], v153, s[12:13] offset:2176
	v_lshlrev_b32_e32 v152, 1, v144
	v_lshl_add_u32 v152, v150, 12, v152
	v_add_u32_e32 v152, 0x0, v152
	global_load_dwordx4 v[240:243], v152, s[14:15]
	v_lshlrev_b32_e32 v152, 1, v144
	v_lshl_add_u32 v152, v150, 12, v152
	v_add_u32_e32 v152, 0x0, v152
	global_load_dwordx4 v[244:247], v152, s[14:15] offset:256
	v_lshlrev_b32_e32 v152, 1, v144
	v_lshl_add_u32 v152, v150, 12, v152
	v_add_u32_e32 v152, 0x10000, v152
	global_load_dwordx4 v[248:251], v152, s[14:15]
	v_lshl_add_u64 v[160:161], s[8:9], 0, v[160:161]
	v_lshl_add_u64 v[160:161], v[160:161], 0, v[142:143]
	s_andn2_b64 vcc, exec, s[40:41]
	s_mov_b64 s[26:27], -1
	s_waitcnt vmcnt(2)
	v_cvt_pk_f32_fp8_e32 v[164:165], v208
	v_cvt_pk_f32_fp8_sdwa v[174:175], v208 src0_sel:WORD_1
	v_cvt_pk_f32_fp8_e32 v[176:177], v209
	v_cvt_pk_f32_fp8_sdwa v[158:159], v209 src0_sel:WORD_1
	v_lshlrev_b32_e32 v178, 16, v240
	v_and_b32_e32 v179, 0xffff0000, v240
	v_lshlrev_b32_e32 v152, 16, v241
	v_and_b32_e32 v153, 0xffff0000, v241
	v_lshlrev_b32_e32 v180, 16, v242
	v_and_b32_e32 v181, 0xffff0000, v242
	v_lshlrev_b32_e32 v154, 16, v243
	v_and_b32_e32 v155, 0xffff0000, v243
	v_pk_fma_f32 v[128:129], v[128:129], v[174:175], v[152:153]
	v_pk_fma_f32 v[152:153], v[124:125], v[158:159], v[154:155]
	v_pk_fma_f32 v[124:125], v[122:123], v[176:177], v[180:181]
	v_pk_fma_f32 v[126:127], v[126:127], v[164:165], v[178:179]
	s_nop 0
	v_cvt_pk_bf16_f32 v122, v126, v127
	v_cvt_pk_bf16_f32 v123, v128, v129
	v_cvt_pk_bf16_f32 v124, v124, v125
	v_cvt_pk_bf16_f32 v125, v152, v153
	global_store_dwordx4 v[160:161], v[122:125], off
	s_nop 1
	v_lshlrev_b32_e32 v122, 1, v144
	v_lshl_add_u32 v122, v150, 12, v122
	v_add_u32_e32 v122, 0x10000, v122
	global_load_dwordx4 v[240:243], v122, s[14:15] offset:256
	s_nop 0
	v_or_b32_e32 v128, 16, v150
	v_lshlrev_b32_e32 v0, 12, v128
	v_lshl_add_u64 v[152:153], s[12:13], 0, v[0:1]
	v_mov_b32_e32 v129, v1
	v_lshlrev_b32_e32 v128, 11, v128
	v_lshl_add_u64 v[152:153], v[152:153], 0, v[144:145]
	v_or_b32_e32 v0, 32, v150
	s_waitcnt vmcnt(3)
	v_cvt_pk_f32_fp8_e32 v[154:155], v210
	v_cvt_pk_f32_fp8_sdwa v[156:157], v210 src0_sel:WORD_1
	v_cvt_pk_f32_fp8_e32 v[158:159], v211
	v_cvt_pk_f32_fp8_sdwa v[126:127], v211 src0_sel:WORD_1
	v_lshlrev_b32_e32 v162, 16, v244
	v_and_b32_e32 v163, 0xffff0000, v244
	v_lshlrev_b32_e32 v122, 16, v245
	v_and_b32_e32 v123, 0xffff0000, v245
	v_lshlrev_b32_e32 v164, 16, v246
	v_and_b32_e32 v165, 0xffff0000, v246
	v_lshlrev_b32_e32 v124, 16, v247
	v_and_b32_e32 v125, 0xffff0000, v247
	v_pk_fma_f32 v[120:121], v[120:121], v[156:157], v[122:123]
	v_pk_fma_f32 v[122:123], v[116:117], v[126:127], v[124:125]
	v_pk_fma_f32 v[116:117], v[114:115], v[158:159], v[164:165]
	v_pk_fma_f32 v[118:119], v[118:119], v[154:155], v[162:163]
	s_nop 0
	v_cvt_pk_bf16_f32 v114, v118, v119
	v_cvt_pk_bf16_f32 v115, v120, v121
	v_cvt_pk_bf16_f32 v116, v116, v117
	v_cvt_pk_bf16_f32 v117, v122, v123
	global_store_dwordx4 v[160:161], v[114:117], off offset:256
	s_nop 1
	v_lshlrev_b32_e32 v114, 1, v144
	v_lshl_add_u32 v114, v150, 12, v114
	v_add_u32_e32 v114, 0x20000, v114
	global_load_dwordx4 v[244:247], v114, s[14:15]
	v_lshlrev_b64 v[120:121], 1, v[128:129]
	v_lshl_add_u64 v[114:115], s[14:15], 0, v[120:121]
	v_lshl_add_u64 v[122:123], v[114:115], 0, v[142:143]
	v_lshl_add_u64 v[120:121], s[8:9], 0, v[120:121]
	v_lshl_add_u64 v[120:121], v[120:121], 0, v[142:143]
	s_waitcnt vmcnt(4)
; #define EGAS __attribute__((address_space(1)))
; __device__ __forceinline__ void ld8f8(const EGAS unsigned char* src, f32x4& v0, f32x4& v1) {
;     typedef float f32x2g __attribute__((ext_vector_type(2)));
;     const u32x2e w = *(const EGAS u32x2e*)src;
;     const f32x2g a = __builtin_amdgcn_cvt_pk_f32_fp8((int)w.x, false), b = __builtin_amdgcn_cvt_pk_f32_fp8((int)w.x, true), c = __builtin_amdgcn_cvt_pk_f32_fp8((int)w.y, false), d = __builtin_amdgcn_cvt_pk_f32_fp8((int)w.y, true);
;     v0 = (f32x4){a.x, a.y, b.x, b.y}; v1 = (f32x4){c.x, c.y, d.x, d.y}; }
; __device__ __forceinline__ void ld8(const EGAS bf16_t* src, f32x4& v0, f32x4& v1) {
;     const u32x4 w = *(const EGAS u32x4*)src;
;     v0[0] = __uint_as_float(w.x << 16); v0[1] = __uint_as_float(w.x & 0xffff0000u); v0[2] = __uint_as_float(w.y << 16); v0[3] = __uint_as_float(w.y & 0xffff0000u);
;     v1[0] = __uint_as_float(w.z << 16); v1[1] = __uint_as_float(w.z & 0xffff0000u); v1[2] = __uint_as_float(w.w << 16); v1[3] = __uint_as_float(w.w & 0xffff0000u); }
;     __device__ __forceinline__ void operator()(const f32x4 (&acc)[2][2][4][2], const Unit& u, int wr, int wc, int fr, int fq) const {
;     ...
;                     } else if constexpr (MODE == EP_YB) {
;                         const int c = pn * 256 + ct; f32x4 g0, g1, t0, t1; ld8f8(WS8(WS_GATES) + row * 4096 + 2048 + c, g0, g1); ld8(WSB(WS_T) + row * 2048 + c, t0, t1);
;                         st8(WSB(WS_MERGED) + row * 2048 + c, t0 + v0 * g0, t1 + v1 * g1);
	v_cvt_pk_f32_fp8_e32 v[124:125], v212
	v_cvt_pk_f32_fp8_sdwa v[126:127], v212 src0_sel:WORD_1
	v_cvt_pk_f32_fp8_e32 v[128:129], v213
	v_cvt_pk_f32_fp8_sdwa v[118:119], v213 src0_sel:WORD_1
	v_lshlrev_b32_e32 v154, 16, v248
	v_and_b32_e32 v155, 0xffff0000, v248
	v_lshlrev_b32_e32 v114, 16, v249
	v_and_b32_e32 v115, 0xffff0000, v249
	v_lshlrev_b32_e32 v156, 16, v250
	v_and_b32_e32 v157, 0xffff0000, v250
	v_lshlrev_b32_e32 v116, 16, v251
	v_and_b32_e32 v117, 0xffff0000, v251
	v_pk_fma_f32 v[112:113], v[112:113], v[126:127], v[114:115]
	v_pk_fma_f32 v[114:115], v[108:109], v[118:119], v[116:117]
	v_pk_fma_f32 v[108:109], v[106:107], v[128:129], v[156:157]
	v_pk_fma_f32 v[110:111], v[110:111], v[124:125], v[154:155]
	s_nop 0
	v_cvt_pk_bf16_f32 v106, v110, v111
	v_cvt_pk_bf16_f32 v107, v112, v113
	v_cvt_pk_bf16_f32 v108, v108, v109
	v_cvt_pk_bf16_f32 v109, v114, v115
	global_store_dwordx4 v[120:121], v[106:109], off
	s_nop 1
	v_lshlrev_b32_e32 v106, 1, v144
	v_lshl_add_u32 v106, v150, 12, v106
	v_add_u32_e32 v106, 0x20000, v106
	global_load_dwordx4 v[248:251], v106, s[14:15] offset:256
	s_nop 0
	v_lshlrev_b32_e32 v112, 11, v0
	v_lshlrev_b32_e32 v0, 12, v0
	v_lshl_add_u64 v[114:115], s[12:13], 0, v[0:1]
	v_mov_b32_e32 v113, v1
	v_lshl_add_u64 v[114:115], v[114:115], 0, v[144:145]
	v_or_b32_e32 v0, 48, v150
	s_waitcnt vmcnt(4)
	v_cvt_pk_f32_fp8_e32 v[116:117], v214
	v_cvt_pk_f32_fp8_sdwa v[118:119], v214 src0_sel:WORD_1
	v_cvt_pk_f32_fp8_e32 v[122:123], v215
	v_cvt_pk_f32_fp8_sdwa v[110:111], v215 src0_sel:WORD_1
	v_lshlrev_b32_e32 v124, 16, v240
	v_and_b32_e32 v125, 0xffff0000, v240
	v_lshlrev_b32_e32 v106, 16, v241
	v_and_b32_e32 v107, 0xffff0000, v241
	v_lshlrev_b32_e32 v126, 16, v242
	v_and_b32_e32 v127, 0xffff0000, v242
	v_lshlrev_b32_e32 v108, 16, v243
	v_and_b32_e32 v109, 0xffff0000, v243
	v_pk_fma_f32 v[104:105], v[104:105], v[118:119], v[106:107]
	v_pk_fma_f32 v[106:107], v[100:101], v[110:111], v[108:109]
	v_pk_fma_f32 v[100:101], v[98:99], v[122:123], v[126:127]
	v_pk_fma_f32 v[102:103], v[102:103], v[116:117], v[124:125]
	s_nop 0
	v_cvt_pk_bf16_f32 v98, v102, v103
	v_cvt_pk_bf16_f32 v99, v104, v105
	v_cvt_pk_bf16_f32 v100, v100, v101
	v_cvt_pk_bf16_f32 v101, v106, v107
	global_store_dwordx4 v[120:121], v[98:101], off offset:256
	s_nop 1
	v_lshlrev_b32_e32 v98, 1, v144
	v_lshl_add_u32 v98, v150, 12, v98
	v_add_u32_e32 v98, 0x30000, v98
	global_load_dwordx4 v[240:243], v98, s[14:15]
	v_lshlrev_b64 v[104:105], 1, v[112:113]
	v_lshl_add_u64 v[98:99], s[14:15], 0, v[104:105]
	v_lshl_add_u64 v[106:107], v[98:99], 0, v[142:143]
	v_lshl_add_u64 v[104:105], s[8:9], 0, v[104:105]
	v_lshl_add_u64 v[104:105], v[104:105], 0, v[142:143]
	s_waitcnt vmcnt(4)
	v_cvt_pk_f32_fp8_e32 v[108:109], v216
	v_cvt_pk_f32_fp8_sdwa v[110:111], v216 src0_sel:WORD_1
	v_cvt_pk_f32_fp8_e32 v[112:113], v217
	v_cvt_pk_f32_fp8_sdwa v[102:103], v217 src0_sel:WORD_1
	v_lshlrev_b32_e32 v116, 16, v244
	v_and_b32_e32 v117, 0xffff0000, v244
	v_lshlrev_b32_e32 v98, 16, v245
	v_and_b32_e32 v99, 0xffff0000, v245
	v_lshlrev_b32_e32 v118, 16, v246
	v_and_b32_e32 v119, 0xffff0000, v246
	v_lshlrev_b32_e32 v100, 16, v247
	v_and_b32_e32 v101, 0xffff0000, v247
	v_pk_fma_f32 v[96:97], v[96:97], v[110:111], v[98:99]
	v_pk_fma_f32 v[98:99], v[92:93], v[102:103], v[100:101]
	v_pk_fma_f32 v[92:93], v[90:91], v[112:113], v[118:119]
	v_pk_fma_f32 v[94:95], v[94:95], v[108:109], v[116:117]
	s_nop 0
	v_cvt_pk_bf16_f32 v90, v94, v95
	v_cvt_pk_bf16_f32 v91, v96, v97
	v_cvt_pk_bf16_f32 v92, v92, v93
	v_cvt_pk_bf16_f32 v93, v98, v99
	global_store_dwordx4 v[104:105], v[90:93], off
	s_nop 1
	v_lshlrev_b32_e32 v90, 1, v144
	v_lshl_add_u32 v90, v150, 12, v90
	v_add_u32_e32 v90, 0x30000, v90
	global_load_dwordx4 v[244:247], v90, s[14:15] offset:256
	s_nop 0
	v_lshlrev_b32_e32 v96, 11, v0
	v_lshlrev_b32_e32 v0, 12, v0
	v_lshl_add_u64 v[98:99], s[12:13], 0, v[0:1]
	v_mov_b32_e32 v97, v1
	v_lshl_add_u64 v[98:99], v[98:99], 0, v[144:145]
	v_add_u32_e32 v0, 0x80, v150
	s_waitcnt vmcnt(4)
	v_cvt_pk_f32_fp8_e32 v[100:101], v218
	v_cvt_pk_f32_fp8_sdwa v[102:103], v218 src0_sel:WORD_1
	v_cvt_pk_f32_fp8_e32 v[106:107], v219
	v_cvt_pk_f32_fp8_sdwa v[94:95], v219 src0_sel:WORD_1
	v_lshlrev_b32_e32 v108, 16, v248
	v_and_b32_e32 v109, 0xffff0000, v248
	v_lshlrev_b32_e32 v90, 16, v249
	v_and_b32_e32 v91, 0xffff0000, v249
	v_lshlrev_b32_e32 v110, 16, v250
	v_and_b32_e32 v111, 0xffff0000, v250
	v_lshlrev_b32_e32 v92, 16, v251
	v_and_b32_e32 v93, 0xffff0000, v251
	v_pk_fma_f32 v[88:89], v[88:89], v[102:103], v[90:91]
	v_pk_fma_f32 v[90:91], v[84:85], v[94:95], v[92:93]
	v_pk_fma_f32 v[84:85], v[82:83], v[106:107], v[110:111]
	v_pk_fma_f32 v[86:87], v[86:87], v[100:101], v[108:109]
	s_nop 0
	v_cvt_pk_bf16_f32 v82, v86, v87
	v_cvt_pk_bf16_f32 v83, v88, v89
	v_cvt_pk_bf16_f32 v84, v84, v85
	v_cvt_pk_bf16_f32 v85, v90, v91
	global_store_dwordx4 v[104:105], v[82:85], off offset:256
	s_nop 1
	v_lshlrev_b32_e32 v82, 1, v144
	v_lshl_add_u32 v82, v150, 12, v82
	v_add_u32_e32 v82, 0x80000, v82
	global_load_dwordx4 v[248:251], v82, s[14:15]
	v_lshlrev_b64 v[88:89], 1, v[96:97]
	v_lshl_add_u64 v[82:83], s[14:15], 0, v[88:89]
	v_lshl_add_u64 v[90:91], v[82:83], 0, v[142:143]
	v_lshl_add_u64 v[88:89], s[8:9], 0, v[88:89]
	v_lshl_add_u64 v[88:89], v[88:89], 0, v[142:143]
	s_waitcnt vmcnt(4)
; #define EGAS __attribute__((address_space(1)))
; __device__ __forceinline__ void ld8f8(const EGAS unsigned char* src, f32x4& v0, f32x4& v1) {
;     typedef float f32x2g __attribute__((ext_vector_type(2)));
;     const u32x2e w = *(const EGAS u32x2e*)src;
;     const f32x2g a = __builtin_amdgcn_cvt_pk_f32_fp8((int)w.x, false), b = __builtin_amdgcn_cvt_pk_f32_fp8((int)w.x, true), c = __builtin_amdgcn_cvt_pk_f32_fp8((int)w.y, false), d = __builtin_amdgcn_cvt_pk_f32_fp8((int)w.y, true);
;     v0 = (f32x4){a.x, a.y, b.x, b.y}; v1 = (f32x4){c.x, c.y, d.x, d.y}; }
; __device__ __forceinline__ void ld8(const EGAS bf16_t* src, f32x4& v0, f32x4& v1) {
;     const u32x4 w = *(const EGAS u32x4*)src;
;     v0[0] = __uint_as_float(w.x << 16); v0[1] = __uint_as_float(w.x & 0xffff0000u); v0[2] = __uint_as_float(w.y << 16); v0[3] = __uint_as_float(w.y & 0xffff0000u);
;     v1[0] = __uint_as_float(w.z << 16); v1[1] = __uint_as_float(w.z & 0xffff0000u); v1[2] = __uint_as_float(w.w << 16); v1[3] = __uint_as_float(w.w & 0xffff0000u); }
;     __device__ __forceinline__ void operator()(const f32x4 (&acc)[2][2][4][2], const Unit& u, int wr, int wc, int fr, int fq) const {
;     ...
;                     } else if constexpr (MODE == EP_YB) {
;                         const int c = pn * 256 + ct; f32x4 g0, g1, t0, t1; ld8f8(WS8(WS_GATES) + row * 4096 + 2048 + c, g0, g1); ld8(WSB(WS_T) + row * 2048 + c, t0, t1);
;                         st8(WSB(WS_MERGED) + row * 2048 + c, t0 + v0 * g0, t1 + v1 * g1);
	v_cvt_pk_f32_fp8_e32 v[92:93], v220
	v_cvt_pk_f32_fp8_sdwa v[94:95], v220 src0_sel:WORD_1
	v_cvt_pk_f32_fp8_e32 v[96:97], v221
	v_cvt_pk_f32_fp8_sdwa v[86:87], v221 src0_sel:WORD_1
	v_lshlrev_b32_e32 v100, 16, v240
	v_and_b32_e32 v101, 0xffff0000, v240
	v_lshlrev_b32_e32 v82, 16, v241
	v_and_b32_e32 v83, 0xffff0000, v241
	v_lshlrev_b32_e32 v102, 16, v242
	v_and_b32_e32 v103, 0xffff0000, v242
	v_lshlrev_b32_e32 v84, 16, v243
	v_and_b32_e32 v85, 0xffff0000, v243
	v_pk_fma_f32 v[80:81], v[80:81], v[94:95], v[82:83]
	v_pk_fma_f32 v[82:83], v[76:77], v[86:87], v[84:85]
	v_pk_fma_f32 v[76:77], v[74:75], v[96:97], v[102:103]
	v_pk_fma_f32 v[78:79], v[78:79], v[92:93], v[100:101]
	s_nop 0
	v_cvt_pk_bf16_f32 v74, v78, v79
	v_cvt_pk_bf16_f32 v75, v80, v81
	v_cvt_pk_bf16_f32 v76, v76, v77
	v_cvt_pk_bf16_f32 v77, v82, v83
	global_store_dwordx4 v[88:89], v[74:77], off
	s_nop 1
	v_lshlrev_b32_e32 v74, 1, v144
	v_lshl_add_u32 v74, v150, 12, v74
	v_add_u32_e32 v74, 0x80000, v74
	global_load_dwordx4 v[240:243], v74, s[14:15] offset:256
	s_nop 0
	v_lshlrev_b32_e32 v80, 11, v0
	v_lshlrev_b32_e32 v0, 12, v0
	v_lshl_add_u64 v[82:83], s[12:13], 0, v[0:1]
	v_mov_b32_e32 v81, v1
	v_lshl_add_u64 v[82:83], v[82:83], 0, v[144:145]
	v_add_u32_e32 v0, 0x90, v150
	s_waitcnt vmcnt(4)
	v_cvt_pk_f32_fp8_e32 v[84:85], v222
	v_cvt_pk_f32_fp8_sdwa v[86:87], v222 src0_sel:WORD_1
	v_cvt_pk_f32_fp8_e32 v[90:91], v223
	v_cvt_pk_f32_fp8_sdwa v[78:79], v223 src0_sel:WORD_1
	v_lshlrev_b32_e32 v92, 16, v244
	v_and_b32_e32 v93, 0xffff0000, v244
	v_lshlrev_b32_e32 v74, 16, v245
	v_and_b32_e32 v75, 0xffff0000, v245
	v_lshlrev_b32_e32 v94, 16, v246
	v_and_b32_e32 v95, 0xffff0000, v246
	v_lshlrev_b32_e32 v76, 16, v247
	v_and_b32_e32 v77, 0xffff0000, v247
	v_pk_fma_f32 v[72:73], v[72:73], v[86:87], v[74:75]
	v_pk_fma_f32 v[74:75], v[68:69], v[78:79], v[76:77]
	v_pk_fma_f32 v[68:69], v[66:67], v[90:91], v[94:95]
	v_pk_fma_f32 v[70:71], v[70:71], v[84:85], v[92:93]
	s_nop 0
	v_cvt_pk_bf16_f32 v66, v70, v71
	v_cvt_pk_bf16_f32 v67, v72, v73
	v_cvt_pk_bf16_f32 v68, v68, v69
	v_cvt_pk_bf16_f32 v69, v74, v75
	global_store_dwordx4 v[88:89], v[66:69], off offset:256
	s_nop 1
	v_lshlrev_b32_e32 v66, 1, v144
	v_lshl_add_u32 v66, v150, 12, v66
	v_add_u32_e32 v66, 0x90000, v66
	global_load_dwordx4 v[244:247], v66, s[14:15]
	v_lshlrev_b64 v[72:73], 1, v[80:81]
	v_lshl_add_u64 v[66:67], s[14:15], 0, v[72:73]
	v_lshl_add_u64 v[74:75], v[66:67], 0, v[142:143]
	v_lshl_add_u64 v[72:73], s[8:9], 0, v[72:73]
	v_lshl_add_u64 v[72:73], v[72:73], 0, v[142:143]
	s_waitcnt vmcnt(4)
	v_cvt_pk_f32_fp8_e32 v[76:77], v224
	v_cvt_pk_f32_fp8_sdwa v[78:79], v224 src0_sel:WORD_1
	v_cvt_pk_f32_fp8_e32 v[80:81], v225
	v_cvt_pk_f32_fp8_sdwa v[70:71], v225 src0_sel:WORD_1
	v_lshlrev_b32_e32 v84, 16, v248
	v_and_b32_e32 v85, 0xffff0000, v248
	v_lshlrev_b32_e32 v66, 16, v249
	v_and_b32_e32 v67, 0xffff0000, v249
	v_lshlrev_b32_e32 v86, 16, v250
	v_and_b32_e32 v87, 0xffff0000, v250
	v_lshlrev_b32_e32 v68, 16, v251
	v_and_b32_e32 v69, 0xffff0000, v251
	v_pk_fma_f32 v[64:65], v[64:65], v[78:79], v[66:67]
	v_pk_fma_f32 v[66:67], v[60:61], v[70:71], v[68:69]
	v_pk_fma_f32 v[60:61], v[58:59], v[80:81], v[86:87]
	v_pk_fma_f32 v[62:63], v[62:63], v[76:77], v[84:85]
	s_nop 0
	v_cvt_pk_bf16_f32 v58, v62, v63
	v_cvt_pk_bf16_f32 v59, v64, v65
	v_cvt_pk_bf16_f32 v60, v60, v61
	v_cvt_pk_bf16_f32 v61, v66, v67
	global_store_dwordx4 v[72:73], v[58:61], off
	s_nop 1
	v_lshlrev_b32_e32 v58, 1, v144
	v_lshl_add_u32 v58, v150, 12, v58
	v_add_u32_e32 v58, 0x90000, v58
	global_load_dwordx4 v[248:251], v58, s[14:15] offset:256
	s_nop 0
	v_lshlrev_b32_e32 v64, 11, v0
	v_lshlrev_b32_e32 v0, 12, v0
	v_lshl_add_u64 v[66:67], s[12:13], 0, v[0:1]
	v_mov_b32_e32 v65, v1
	v_lshl_add_u64 v[66:67], v[66:67], 0, v[144:145]
	v_add_u32_e32 v0, 0xa0, v150
	s_waitcnt vmcnt(4)
	v_cvt_pk_f32_fp8_e32 v[68:69], v226
	v_cvt_pk_f32_fp8_sdwa v[70:71], v226 src0_sel:WORD_1
	v_cvt_pk_f32_fp8_e32 v[74:75], v227
	v_cvt_pk_f32_fp8_sdwa v[62:63], v227 src0_sel:WORD_1
	v_lshlrev_b32_e32 v76, 16, v240
	v_and_b32_e32 v77, 0xffff0000, v240
	v_lshlrev_b32_e32 v58, 16, v241
	v_and_b32_e32 v59, 0xffff0000, v241
	v_lshlrev_b32_e32 v78, 16, v242
	v_and_b32_e32 v79, 0xffff0000, v242
	v_lshlrev_b32_e32 v60, 16, v243
	v_and_b32_e32 v61, 0xffff0000, v243
	v_pk_fma_f32 v[56:57], v[56:57], v[70:71], v[58:59]
	v_pk_fma_f32 v[58:59], v[52:53], v[62:63], v[60:61]
	v_pk_fma_f32 v[52:53], v[50:51], v[74:75], v[78:79]
	v_pk_fma_f32 v[54:55], v[54:55], v[68:69], v[76:77]
	s_nop 0
	v_cvt_pk_bf16_f32 v50, v54, v55
	v_cvt_pk_bf16_f32 v51, v56, v57
	v_cvt_pk_bf16_f32 v52, v52, v53
	v_cvt_pk_bf16_f32 v53, v58, v59
	global_store_dwordx4 v[72:73], v[50:53], off offset:256
	s_nop 1
	v_lshlrev_b32_e32 v50, 1, v144
	v_lshl_add_u32 v50, v150, 12, v50
	v_add_u32_e32 v50, 0xa0000, v50
	global_load_dwordx4 v[240:243], v50, s[14:15]
	v_lshlrev_b64 v[56:57], 1, v[64:65]
	v_lshl_add_u64 v[50:51], s[14:15], 0, v[56:57]
	v_lshl_add_u64 v[58:59], v[50:51], 0, v[142:143]
	v_lshl_add_u64 v[56:57], s[8:9], 0, v[56:57]
	v_lshl_add_u64 v[56:57], v[56:57], 0, v[142:143]
	s_waitcnt vmcnt(4)
; #define EGAS __attribute__((address_space(1)))
; __device__ __forceinline__ void ld8f8(const EGAS unsigned char* src, f32x4& v0, f32x4& v1) {
;     typedef float f32x2g __attribute__((ext_vector_type(2)));
;     const u32x2e w = *(const EGAS u32x2e*)src;
;     const f32x2g a = __builtin_amdgcn_cvt_pk_f32_fp8((int)w.x, false), b = __builtin_amdgcn_cvt_pk_f32_fp8((int)w.x, true), c = __builtin_amdgcn_cvt_pk_f32_fp8((int)w.y, false), d = __builtin_amdgcn_cvt_pk_f32_fp8((int)w.y, true);
;     v0 = (f32x4){a.x, a.y, b.x, b.y}; v1 = (f32x4){c.x, c.y, d.x, d.y}; }
; __device__ __forceinline__ void ld8(const EGAS bf16_t* src, f32x4& v0, f32x4& v1) {
;     const u32x4 w = *(const EGAS u32x4*)src;
;     v0[0] = __uint_as_float(w.x << 16); v0[1] = __uint_as_float(w.x & 0xffff0000u); v0[2] = __uint_as_float(w.y << 16); v0[3] = __uint_as_float(w.y & 0xffff0000u);
;     v1[0] = __uint_as_float(w.z << 16); v1[1] = __uint_as_float(w.z & 0xffff0000u); v1[2] = __uint_as_float(w.w << 16); v1[3] = __uint_as_float(w.w & 0xffff0000u); }
;     __device__ __forceinline__ void operator()(const f32x4 (&acc)[2][2][4][2], const Unit& u, int wr, int wc, int fr, int fq) const {
;     ...
;                     } else if constexpr (MODE == EP_YB) {
;                         const int c = pn * 256 + ct; f32x4 g0, g1, t0, t1; ld8f8(WS8(WS_GATES) + row * 4096 + 2048 + c, g0, g1); ld8(WSB(WS_T) + row * 2048 + c, t0, t1);
;                         st8(WSB(WS_MERGED) + row * 2048 + c, t0 + v0 * g0, t1 + v1 * g1);
	v_cvt_pk_f32_fp8_e32 v[60:61], v228
	v_cvt_pk_f32_fp8_sdwa v[62:63], v228 src0_sel:WORD_1
	v_cvt_pk_f32_fp8_e32 v[64:65], v229
	v_cvt_pk_f32_fp8_sdwa v[54:55], v229 src0_sel:WORD_1
	v_lshlrev_b32_e32 v68, 16, v244
	v_and_b32_e32 v69, 0xffff0000, v244
	v_lshlrev_b32_e32 v50, 16, v245
	v_and_b32_e32 v51, 0xffff0000, v245
	v_lshlrev_b32_e32 v70, 16, v246
	v_and_b32_e32 v71, 0xffff0000, v246
	v_lshlrev_b32_e32 v52, 16, v247
	v_and_b32_e32 v53, 0xffff0000, v247
	v_pk_fma_f32 v[48:49], v[48:49], v[62:63], v[50:51]
	v_pk_fma_f32 v[50:51], v[44:45], v[54:55], v[52:53]
	v_pk_fma_f32 v[44:45], v[42:43], v[64:65], v[70:71]
	v_pk_fma_f32 v[46:47], v[46:47], v[60:61], v[68:69]
	s_nop 0
	v_cvt_pk_bf16_f32 v42, v46, v47
	v_cvt_pk_bf16_f32 v43, v48, v49
	v_cvt_pk_bf16_f32 v44, v44, v45
	v_cvt_pk_bf16_f32 v45, v50, v51
	global_store_dwordx4 v[56:57], v[42:45], off
	s_nop 1
	v_lshlrev_b32_e32 v42, 1, v144
	v_lshl_add_u32 v42, v150, 12, v42
	v_add_u32_e32 v42, 0xa0000, v42
	global_load_dwordx4 v[244:247], v42, s[14:15] offset:256
	s_nop 0
	v_lshlrev_b32_e32 v48, 11, v0
	v_lshlrev_b32_e32 v0, 12, v0
	v_lshl_add_u64 v[50:51], s[12:13], 0, v[0:1]
	v_mov_b32_e32 v49, v1
	v_lshl_add_u64 v[50:51], v[50:51], 0, v[144:145]
	v_add_u32_e32 v0, 0xb0, v150
	s_waitcnt vmcnt(4)
	v_cvt_pk_f32_fp8_e32 v[52:53], v230
	v_cvt_pk_f32_fp8_sdwa v[54:55], v230 src0_sel:WORD_1
	v_cvt_pk_f32_fp8_e32 v[58:59], v231
	v_cvt_pk_f32_fp8_sdwa v[46:47], v231 src0_sel:WORD_1
	v_lshlrev_b32_e32 v60, 16, v248
	v_and_b32_e32 v61, 0xffff0000, v248
	v_lshlrev_b32_e32 v42, 16, v249
	v_and_b32_e32 v43, 0xffff0000, v249
	v_lshlrev_b32_e32 v62, 16, v250
	v_and_b32_e32 v63, 0xffff0000, v250
	v_lshlrev_b32_e32 v44, 16, v251
	v_and_b32_e32 v45, 0xffff0000, v251
	v_pk_fma_f32 v[40:41], v[40:41], v[54:55], v[42:43]
	v_pk_fma_f32 v[42:43], v[36:37], v[46:47], v[44:45]
	v_pk_fma_f32 v[36:37], v[34:35], v[58:59], v[62:63]
	v_pk_fma_f32 v[38:39], v[38:39], v[52:53], v[60:61]
	s_nop 0
	v_cvt_pk_bf16_f32 v34, v38, v39
	v_cvt_pk_bf16_f32 v35, v40, v41
	v_cvt_pk_bf16_f32 v36, v36, v37
	v_cvt_pk_bf16_f32 v37, v42, v43
	global_store_dwordx4 v[56:57], v[34:37], off offset:256
	s_nop 1
	v_lshlrev_b32_e32 v34, 1, v144
	v_lshl_add_u32 v34, v150, 12, v34
	v_add_u32_e32 v34, 0xb0000, v34
	global_load_dwordx4 v[248:251], v34, s[14:15]
	v_lshlrev_b64 v[40:41], 1, v[48:49]
	v_lshl_add_u64 v[34:35], s[14:15], 0, v[40:41]
	v_lshl_add_u64 v[42:43], v[34:35], 0, v[142:143]
	v_lshl_add_u64 v[40:41], s[8:9], 0, v[40:41]
	v_lshl_add_u64 v[40:41], v[40:41], 0, v[142:143]
	s_waitcnt vmcnt(4)
	v_cvt_pk_f32_fp8_e32 v[44:45], v232
	v_cvt_pk_f32_fp8_sdwa v[46:47], v232 src0_sel:WORD_1
	v_cvt_pk_f32_fp8_e32 v[48:49], v233
	v_cvt_pk_f32_fp8_sdwa v[38:39], v233 src0_sel:WORD_1
	v_lshlrev_b32_e32 v52, 16, v240
	v_and_b32_e32 v53, 0xffff0000, v240
	v_lshlrev_b32_e32 v34, 16, v241
	v_and_b32_e32 v35, 0xffff0000, v241
	v_lshlrev_b32_e32 v54, 16, v242
	v_and_b32_e32 v55, 0xffff0000, v242
	v_lshlrev_b32_e32 v36, 16, v243
	v_and_b32_e32 v37, 0xffff0000, v243
	v_pk_fma_f32 v[32:33], v[32:33], v[46:47], v[34:35]
	v_pk_fma_f32 v[34:35], v[28:29], v[38:39], v[36:37]
	v_pk_fma_f32 v[28:29], v[26:27], v[48:49], v[54:55]
	v_pk_fma_f32 v[30:31], v[30:31], v[44:45], v[52:53]
	s_nop 0
	v_cvt_pk_bf16_f32 v26, v30, v31
	v_cvt_pk_bf16_f32 v27, v32, v33
	v_cvt_pk_bf16_f32 v28, v28, v29
	v_cvt_pk_bf16_f32 v29, v34, v35
	global_store_dwordx4 v[40:41], v[26:29], off
	s_nop 1
	v_lshlrev_b32_e32 v26, 1, v144
	v_lshl_add_u32 v26, v150, 12, v26
	v_add_u32_e32 v26, 0xb0000, v26
	global_load_dwordx4 v[240:243], v26, s[14:15] offset:256
	s_nop 0
	v_lshlrev_b32_e32 v32, 11, v0
	v_lshlrev_b32_e32 v0, 12, v0
	v_lshl_add_u64 v[34:35], s[12:13], 0, v[0:1]
	v_mov_b32_e32 v33, v1
	v_lshl_add_u64 v[34:35], v[34:35], 0, v[144:145]
	s_waitcnt vmcnt(4)
	v_cvt_pk_f32_fp8_e32 v[36:37], v234
	v_cvt_pk_f32_fp8_sdwa v[38:39], v234 src0_sel:WORD_1
	v_cvt_pk_f32_fp8_e32 v[42:43], v235
	v_cvt_pk_f32_fp8_sdwa v[30:31], v235 src0_sel:WORD_1
	v_lshlrev_b32_e32 v44, 16, v244
	v_and_b32_e32 v45, 0xffff0000, v244
	v_lshlrev_b32_e32 v26, 16, v245
	v_and_b32_e32 v27, 0xffff0000, v245
	v_lshlrev_b32_e32 v46, 16, v246
	v_and_b32_e32 v47, 0xffff0000, v246
	v_lshlrev_b32_e32 v28, 16, v247
	v_and_b32_e32 v29, 0xffff0000, v247
	v_pk_fma_f32 v[24:25], v[24:25], v[38:39], v[26:27]
	v_pk_fma_f32 v[26:27], v[20:21], v[30:31], v[28:29]
	v_pk_fma_f32 v[20:21], v[18:19], v[42:43], v[46:47]
	v_pk_fma_f32 v[22:23], v[22:23], v[36:37], v[44:45]
	s_nop 0
	v_cvt_pk_bf16_f32 v18, v22, v23
	v_cvt_pk_bf16_f32 v19, v24, v25
	v_cvt_pk_bf16_f32 v20, v20, v21
	v_cvt_pk_bf16_f32 v21, v26, v27
	global_store_dwordx4 v[40:41], v[18:21], off offset:256
	v_lshlrev_b64 v[24:25], 1, v[32:33]
	v_lshl_add_u64 v[18:19], s[14:15], 0, v[24:25]
	v_lshl_add_u64 v[26:27], v[18:19], 0, v[142:143]
	v_lshl_add_u64 v[24:25], s[8:9], 0, v[24:25]
	v_lshl_add_u64 v[24:25], v[24:25], 0, v[142:143]
	s_waitcnt vmcnt(3)
	v_cvt_pk_f32_fp8_e32 v[28:29], v236
	v_cvt_pk_f32_fp8_sdwa v[30:31], v236 src0_sel:WORD_1
	v_cvt_pk_f32_fp8_e32 v[32:33], v237
	v_cvt_pk_f32_fp8_sdwa v[22:23], v237 src0_sel:WORD_1
	v_lshlrev_b32_e32 v36, 16, v248
	v_and_b32_e32 v37, 0xffff0000, v248
	v_lshlrev_b32_e32 v18, 16, v249
	v_and_b32_e32 v19, 0xffff0000, v249
	v_lshlrev_b32_e32 v38, 16, v250
	v_and_b32_e32 v39, 0xffff0000, v250
	v_lshlrev_b32_e32 v20, 16, v251
	v_and_b32_e32 v21, 0xffff0000, v251
	v_pk_fma_f32 v[16:17], v[16:17], v[30:31], v[18:19]
	v_pk_fma_f32 v[18:19], v[12:13], v[22:23], v[20:21]
	v_pk_fma_f32 v[12:13], v[10:11], v[32:33], v[38:39]
	v_pk_fma_f32 v[14:15], v[14:15], v[28:29], v[36:37]
	s_nop 0
	v_cvt_pk_bf16_f32 v10, v14, v15
	v_cvt_pk_bf16_f32 v11, v16, v17
	v_cvt_pk_bf16_f32 v12, v12, v13
	v_cvt_pk_bf16_f32 v13, v18, v19
	global_store_dwordx4 v[24:25], v[10:13], off
	s_nop 0
	s_waitcnt vmcnt(2)
	v_cvt_pk_f32_fp8_e32 v[16:17], v238
	v_cvt_pk_f32_fp8_sdwa v[18:19], v238 src0_sel:WORD_1
	v_cvt_pk_f32_fp8_e32 v[20:21], v239
	v_cvt_pk_f32_fp8_sdwa v[14:15], v239 src0_sel:WORD_1
	v_lshlrev_b32_e32 v22, 16, v240
	v_and_b32_e32 v23, 0xffff0000, v240
	v_lshlrev_b32_e32 v10, 16, v241
	v_and_b32_e32 v11, 0xffff0000, v241
	v_lshlrev_b32_e32 v26, 16, v242
	v_and_b32_e32 v27, 0xffff0000, v242
	v_lshlrev_b32_e32 v12, 16, v243
	v_and_b32_e32 v13, 0xffff0000, v243
	v_pk_fma_f32 v[8:9], v[8:9], v[18:19], v[10:11]
	v_pk_fma_f32 v[10:11], v[4:5], v[14:15], v[12:13]
	v_pk_fma_f32 v[4:5], v[2:3], v[20:21], v[26:27]
	v_pk_fma_f32 v[6:7], v[6:7], v[16:17], v[22:23]
	s_nop 0
	v_cvt_pk_bf16_f32 v2, v6, v7
	v_cvt_pk_bf16_f32 v3, v8, v9
	v_cvt_pk_bf16_f32 v4, v4, v5
	v_cvt_pk_bf16_f32 v5, v10, v11
	global_store_dwordx4 v[24:25], v[2:5], off offset:256
	s_cbranch_vccnz .LBB0_1442
	s_andn2_b64 vcc, exec, s[10:11]
	s_cbranch_vccnz .LBB0_1441
	s_barrier
	s_branch .LBB0_1441

; #define EGAS __attribute__((address_space(1)))
; __device__ __forceinline__ void ld8(const EGAS bf16_t* src, f32x4& v0, f32x4& v1) {
;     const u32x4 w = *(const EGAS u32x4*)src;
;     v0[0] = __uint_as_float(w.x << 16); v0[1] = __uint_as_float(w.x & 0xffff0000u); v0[2] = __uint_as_float(w.y << 16); v0[3] = __uint_as_float(w.y & 0xffff0000u);
;     v1[0] = __uint_as_float(w.z << 16); v1[1] = __uint_as_float(w.z & 0xffff0000u); v1[2] = __uint_as_float(w.w << 16); v1[3] = __uint_as_float(w.w & 0xffff0000u); }
;     __device__ __forceinline__ void operator()(const f32x4 (&acc)[2][2][4][2], const Unit& u, int wr, int wc, int fr, int fq) const {
;     ...
;                     } else if constexpr (MODE == EP_RES) {
;                         const int c = pn * 256 + ct; EGAS bf16_t* xb = (EGAS bf16_t*)((EGAS unsigned char*)p.fo + 67108864) + row * 2048 + c; f32x4 x0, x1;
;                         if (p.f0) { const EGAS float* xi = (const EGAS float*)p.f0 + row * 2048 + c; x0 = *(const EGAS f32x4*)xi; x1 = *(const EGAS f32x4*)(xi + 4); } else ld8(xb, x0, x1);
;                         st8(xb, x0 + v0, x1 + v1);
.LBB0_1922:
	v_lshl_or_b32 v142, s47, 8, v146
	v_lshl_add_u32 v0, s45, 19, v145
	v_ashrrev_i32_e32 v143, 31, v142
	v_lshl_add_u64 v[148:149], v[0:1], 1, s[8:9]
	v_lshlrev_b64 v[142:143], 1, v[142:143]
	v_lshl_add_u64 v[152:153], v[148:149], 0, v[142:143]
	v_lshl_add_u32 v248, v0, 1, v142
	global_load_dwordx4 v[208:211], v248, s[8:9]
	global_load_dwordx4 v[212:215], v248, s[8:9] offset:256
	v_add_u32_e32 v249, 0x10000, v248
	global_load_dwordx4 v[216:219], v249, s[8:9]
	v_add_u32_e32 v249, 0x10000, v248
	global_load_dwordx4 v[220:223], v249, s[8:9] offset:256
	v_add_u32_e32 v249, 0x20000, v248
	global_load_dwordx4 v[224:227], v249, s[8:9]
	v_add_u32_e32 v249, 0x20000, v248
	global_load_dwordx4 v[228:231], v249, s[8:9] offset:256
	v_add_u32_e32 v249, 0x30000, v248
	global_load_dwordx4 v[232:235], v249, s[8:9]
	v_add_u32_e32 v249, 0x30000, v248
	global_load_dwordx4 v[236:239], v249, s[8:9] offset:256
	v_add_u32_e32 v249, 0x80000, v248
	global_load_dwordx4 v[240:243], v249, s[8:9]
	v_add_u32_e32 v249, 0x80000, v248
	global_load_dwordx4 v[244:247], v249, s[8:9] offset:256
	s_and_b64 vcc, exec, s[40:41]
	s_mov_b64 s[14:15], -1
	s_waitcnt vmcnt(9)
	v_lshlrev_b32_e32 v154, 16, v208
	v_and_b32_e32 v155, 0xffff0000, v208
	v_lshlrev_b32_e32 v148, 16, v209
	v_and_b32_e32 v149, 0xffff0000, v209
	v_lshlrev_b32_e32 v156, 16, v210
	v_and_b32_e32 v157, 0xffff0000, v210
	v_lshlrev_b32_e32 v150, 16, v211
	v_and_b32_e32 v151, 0xffff0000, v211
	v_pk_add_f32 v[128:129], v[128:129], v[148:149]
	v_pk_add_f32 v[126:127], v[126:127], v[154:155]
	v_pk_add_f32 v[148:149], v[124:125], v[150:151]
	v_pk_add_f32 v[124:125], v[122:123], v[156:157]
	v_cvt_pk_bf16_f32 v122, v126, v127
	v_cvt_pk_bf16_f32 v123, v128, v129
	s_nop 0
	v_cvt_pk_bf16_f32 v124, v124, v125
	v_cvt_pk_bf16_f32 v125, v148, v149
	v_mov_b32_e32 v149, v1
	v_or_b32_e32 v148, 0x8000, v0
	v_lshl_add_u64 v[148:149], v[148:149], 1, s[8:9]
	global_store_dwordx4 v[152:153], v[122:125], off
	s_nop 1
	v_add_u32_e32 v249, 0x90000, v248
	global_load_dwordx4 v[208:211], v249, s[8:9]
	v_lshl_add_u64 v[148:149], v[148:149], 0, v[142:143]
	s_waitcnt vmcnt(10)
	v_lshlrev_b32_e32 v122, 16, v212
	v_and_b32_e32 v123, 0xffff0000, v212
	v_lshlrev_b32_e32 v124, 16, v213
	v_and_b32_e32 v125, 0xffff0000, v213
	v_lshlrev_b32_e32 v126, 16, v214
	v_and_b32_e32 v127, 0xffff0000, v214
	v_lshlrev_b32_e32 v128, 16, v215
	v_and_b32_e32 v129, 0xffff0000, v215
	v_pk_add_f32 v[116:117], v[116:117], v[124:125]
	v_pk_add_f32 v[114:115], v[114:115], v[122:123]
	v_pk_add_f32 v[122:123], v[112:113], v[128:129]
	v_pk_add_f32 v[112:113], v[110:111], v[126:127]
	v_cvt_pk_bf16_f32 v110, v114, v115
	v_cvt_pk_bf16_f32 v111, v116, v117
	s_nop 0
	v_cvt_pk_bf16_f32 v112, v112, v113
	v_cvt_pk_bf16_f32 v113, v122, v123
	s_nop 0
	global_store_dwordx4 v[152:153], v[110:113], off offset:256
	s_nop 1
	v_add_u32_e32 v249, 0x90000, v248
	global_load_dwordx4 v[212:215], v249, s[8:9] offset:256
	s_waitcnt vmcnt(11)
	s_nop 0
	v_lshlrev_b32_e32 v110, 16, v216
	v_and_b32_e32 v111, 0xffff0000, v216
	v_lshlrev_b32_e32 v112, 16, v217
	v_and_b32_e32 v113, 0xffff0000, v217
	v_lshlrev_b32_e32 v114, 16, v218
	v_and_b32_e32 v115, 0xffff0000, v218
	v_lshlrev_b32_e32 v116, 16, v219
	v_and_b32_e32 v117, 0xffff0000, v219
	v_pk_add_f32 v[112:113], v[120:121], v[112:113]
	v_pk_add_f32 v[110:111], v[118:119], v[110:111]
	v_pk_add_f32 v[116:117], v[108:109], v[116:117]
	v_pk_add_f32 v[108:109], v[106:107], v[114:115]
	v_cvt_pk_bf16_f32 v106, v110, v111
	v_cvt_pk_bf16_f32 v107, v112, v113
	v_mov_b32_e32 v115, v1
	v_cvt_pk_bf16_f32 v108, v108, v109
	v_cvt_pk_bf16_f32 v109, v116, v117
	v_or_b32_e32 v114, 0x10000, v0
	v_lshl_add_u64 v[114:115], v[114:115], 1, s[8:9]
	global_store_dwordx4 v[148:149], v[106:109], off
	s_nop 1
	v_add_u32_e32 v249, 0xa0000, v248
	global_load_dwordx4 v[216:219], v249, s[8:9]
	v_lshl_add_u64 v[114:115], v[114:115], 0, v[142:143]
	s_waitcnt vmcnt(12)
	v_lshlrev_b32_e32 v106, 16, v220
	v_and_b32_e32 v107, 0xffff0000, v220
	v_lshlrev_b32_e32 v108, 16, v221
	v_and_b32_e32 v109, 0xffff0000, v221
	v_lshlrev_b32_e32 v110, 16, v222
	v_and_b32_e32 v111, 0xffff0000, v222
	v_lshlrev_b32_e32 v112, 16, v223
	v_and_b32_e32 v113, 0xffff0000, v223
	v_pk_add_f32 v[100:101], v[100:101], v[108:109]
	v_pk_add_f32 v[98:99], v[98:99], v[106:107]
	v_pk_add_f32 v[106:107], v[96:97], v[112:113]
	v_pk_add_f32 v[96:97], v[94:95], v[110:111]
	v_cvt_pk_bf16_f32 v94, v98, v99
	v_cvt_pk_bf16_f32 v95, v100, v101
	s_nop 0
	v_cvt_pk_bf16_f32 v96, v96, v97
	v_cvt_pk_bf16_f32 v97, v106, v107
	s_nop 0
	global_store_dwordx4 v[148:149], v[94:97], off offset:256
	s_nop 1
	v_add_u32_e32 v249, 0xa0000, v248
	global_load_dwordx4 v[220:223], v249, s[8:9] offset:256
	s_waitcnt vmcnt(13)
	s_nop 0
	v_lshlrev_b32_e32 v94, 16, v224
	v_and_b32_e32 v95, 0xffff0000, v224
	v_lshlrev_b32_e32 v96, 16, v225
	v_and_b32_e32 v97, 0xffff0000, v225
	v_lshlrev_b32_e32 v98, 16, v226
	v_and_b32_e32 v99, 0xffff0000, v226
	v_lshlrev_b32_e32 v100, 16, v227
	v_and_b32_e32 v101, 0xffff0000, v227
	v_pk_add_f32 v[96:97], v[104:105], v[96:97]
	v_pk_add_f32 v[94:95], v[102:103], v[94:95]
	v_pk_add_f32 v[100:101], v[92:93], v[100:101]
	v_pk_add_f32 v[92:93], v[90:91], v[98:99]
	v_cvt_pk_bf16_f32 v90, v94, v95
	v_cvt_pk_bf16_f32 v91, v96, v97
	v_mov_b32_e32 v99, v1
	v_cvt_pk_bf16_f32 v92, v92, v93
	v_cvt_pk_bf16_f32 v93, v100, v101
	v_or_b32_e32 v98, 0x18000, v0
	v_lshl_add_u64 v[98:99], v[98:99], 1, s[8:9]
	global_store_dwordx4 v[114:115], v[90:93], off
	s_nop 1
	v_add_u32_e32 v249, 0xb0000, v248
	global_load_dwordx4 v[224:227], v249, s[8:9]
	v_lshl_add_u64 v[98:99], v[98:99], 0, v[142:143]
	s_waitcnt vmcnt(14)
; #define EGAS __attribute__((address_space(1)))
; __device__ __forceinline__ void ld8(const EGAS bf16_t* src, f32x4& v0, f32x4& v1) {
;     const u32x4 w = *(const EGAS u32x4*)src;
;     v0[0] = __uint_as_float(w.x << 16); v0[1] = __uint_as_float(w.x & 0xffff0000u); v0[2] = __uint_as_float(w.y << 16); v0[3] = __uint_as_float(w.y & 0xffff0000u);
;     v1[0] = __uint_as_float(w.z << 16); v1[1] = __uint_as_float(w.z & 0xffff0000u); v1[2] = __uint_as_float(w.w << 16); v1[3] = __uint_as_float(w.w & 0xffff0000u); }
;     __device__ __forceinline__ void operator()(const f32x4 (&acc)[2][2][4][2], const Unit& u, int wr, int wc, int fr, int fq) const {
;     ...
;                     } else if constexpr (MODE == EP_RES) {
;                         const int c = pn * 256 + ct; EGAS bf16_t* xb = (EGAS bf16_t*)((EGAS unsigned char*)p.fo + 67108864) + row * 2048 + c; f32x4 x0, x1;
;                         if (p.f0) { const EGAS float* xi = (const EGAS float*)p.f0 + row * 2048 + c; x0 = *(const EGAS f32x4*)xi; x1 = *(const EGAS f32x4*)(xi + 4); } else ld8(xb, x0, x1);
;                         st8(xb, x0 + v0, x1 + v1);
	v_lshlrev_b32_e32 v90, 16, v228
	v_and_b32_e32 v91, 0xffff0000, v228
	v_lshlrev_b32_e32 v92, 16, v229
	v_and_b32_e32 v93, 0xffff0000, v229
	v_lshlrev_b32_e32 v94, 16, v230
	v_and_b32_e32 v95, 0xffff0000, v230
	v_lshlrev_b32_e32 v96, 16, v231
	v_and_b32_e32 v97, 0xffff0000, v231
	v_pk_add_f32 v[84:85], v[84:85], v[92:93]
	v_pk_add_f32 v[82:83], v[82:83], v[90:91]
	v_pk_add_f32 v[90:91], v[80:81], v[96:97]
	v_pk_add_f32 v[80:81], v[78:79], v[94:95]
	v_cvt_pk_bf16_f32 v78, v82, v83
	v_cvt_pk_bf16_f32 v79, v84, v85
	s_nop 0
	v_cvt_pk_bf16_f32 v80, v80, v81
	v_cvt_pk_bf16_f32 v81, v90, v91
	s_nop 0
	global_store_dwordx4 v[114:115], v[78:81], off offset:256
	s_nop 1
	v_add_u32_e32 v249, 0xb0000, v248
	global_load_dwordx4 v[228:231], v249, s[8:9] offset:256
	s_waitcnt vmcnt(15)
	s_nop 0
	v_lshlrev_b32_e32 v78, 16, v232
	v_and_b32_e32 v79, 0xffff0000, v232
	v_lshlrev_b32_e32 v80, 16, v233
	v_and_b32_e32 v81, 0xffff0000, v233
	v_lshlrev_b32_e32 v82, 16, v234
	v_and_b32_e32 v83, 0xffff0000, v234
	v_lshlrev_b32_e32 v84, 16, v235
	v_and_b32_e32 v85, 0xffff0000, v235
	v_pk_add_f32 v[80:81], v[88:89], v[80:81]
	v_pk_add_f32 v[78:79], v[86:87], v[78:79]
	v_pk_add_f32 v[84:85], v[76:77], v[84:85]
	v_pk_add_f32 v[76:77], v[74:75], v[82:83]
	v_cvt_pk_bf16_f32 v74, v78, v79
	v_cvt_pk_bf16_f32 v75, v80, v81
	v_mov_b32_e32 v83, v1
	v_cvt_pk_bf16_f32 v76, v76, v77
	v_cvt_pk_bf16_f32 v77, v84, v85
	v_add_u32_e32 v82, 0x40000, v0
	v_lshl_add_u64 v[82:83], v[82:83], 1, s[8:9]
	global_store_dwordx4 v[98:99], v[74:77], off
	v_lshl_add_u64 v[82:83], v[82:83], 0, v[142:143]
	s_waitcnt vmcnt(15)
	v_lshlrev_b32_e32 v74, 16, v236
	v_and_b32_e32 v75, 0xffff0000, v236
	v_lshlrev_b32_e32 v76, 16, v237
	v_and_b32_e32 v77, 0xffff0000, v237
	v_lshlrev_b32_e32 v78, 16, v238
	v_and_b32_e32 v79, 0xffff0000, v238
	v_lshlrev_b32_e32 v80, 16, v239
	v_and_b32_e32 v81, 0xffff0000, v239
	v_pk_add_f32 v[72:73], v[72:73], v[76:77]
	v_pk_add_f32 v[70:71], v[70:71], v[74:75]
	v_pk_add_f32 v[74:75], v[68:69], v[80:81]
	v_pk_add_f32 v[68:69], v[66:67], v[78:79]
	v_cvt_pk_bf16_f32 v66, v70, v71
	v_cvt_pk_bf16_f32 v67, v72, v73
	s_nop 0
	v_cvt_pk_bf16_f32 v68, v68, v69
	v_cvt_pk_bf16_f32 v69, v74, v75
	s_nop 0
	global_store_dwordx4 v[98:99], v[66:69], off offset:256
	s_waitcnt vmcnt(15)
	s_nop 0
	v_lshlrev_b32_e32 v66, 16, v240
	v_and_b32_e32 v67, 0xffff0000, v240
	v_lshlrev_b32_e32 v68, 16, v241
	v_and_b32_e32 v69, 0xffff0000, v241
	v_lshlrev_b32_e32 v70, 16, v242
	v_and_b32_e32 v71, 0xffff0000, v242
	v_lshlrev_b32_e32 v72, 16, v243
	v_and_b32_e32 v73, 0xffff0000, v243
	v_pk_add_f32 v[64:65], v[64:65], v[68:69]
	v_pk_add_f32 v[62:63], v[62:63], v[66:67]
	v_pk_add_f32 v[66:67], v[60:61], v[72:73]
	v_pk_add_f32 v[60:61], v[58:59], v[70:71]
	v_cvt_pk_bf16_f32 v58, v62, v63
	v_cvt_pk_bf16_f32 v59, v64, v65
	s_nop 0
	v_cvt_pk_bf16_f32 v60, v60, v61
	v_cvt_pk_bf16_f32 v61, v66, v67
	v_mov_b32_e32 v67, v1
	v_add_u32_e32 v66, 0x48000, v0
	v_lshl_add_u64 v[66:67], v[66:67], 1, s[8:9]
	global_store_dwordx4 v[82:83], v[58:61], off
	v_lshl_add_u64 v[66:67], v[66:67], 0, v[142:143]
	s_waitcnt vmcnt(15)
	v_lshlrev_b32_e32 v58, 16, v244
	v_and_b32_e32 v59, 0xffff0000, v244
	v_lshlrev_b32_e32 v60, 16, v245
	v_and_b32_e32 v61, 0xffff0000, v245
	v_lshlrev_b32_e32 v62, 16, v246
	v_and_b32_e32 v63, 0xffff0000, v246
	v_lshlrev_b32_e32 v64, 16, v247
	v_and_b32_e32 v65, 0xffff0000, v247
	v_pk_add_f32 v[52:53], v[52:53], v[60:61]
	v_pk_add_f32 v[50:51], v[50:51], v[58:59]
	v_pk_add_f32 v[58:59], v[48:49], v[64:65]
	v_pk_add_f32 v[48:49], v[46:47], v[62:63]
	v_cvt_pk_bf16_f32 v46, v50, v51
	v_cvt_pk_bf16_f32 v47, v52, v53
	s_nop 0
	v_cvt_pk_bf16_f32 v48, v48, v49
	v_cvt_pk_bf16_f32 v49, v58, v59
	s_nop 0
	global_store_dwordx4 v[82:83], v[46:49], off offset:256
	s_waitcnt vmcnt(14)
; #define EGAS __attribute__((address_space(1)))
; __device__ __forceinline__ void ld8(const EGAS bf16_t* src, f32x4& v0, f32x4& v1) {
;     const u32x4 w = *(const EGAS u32x4*)src;
;     v0[0] = __uint_as_float(w.x << 16); v0[1] = __uint_as_float(w.x & 0xffff0000u); v0[2] = __uint_as_float(w.y << 16); v0[3] = __uint_as_float(w.y & 0xffff0000u);
;     v1[0] = __uint_as_float(w.z << 16); v1[1] = __uint_as_float(w.z & 0xffff0000u); v1[2] = __uint_as_float(w.w << 16); v1[3] = __uint_as_float(w.w & 0xffff0000u); }
;     __device__ __forceinline__ void operator()(const f32x4 (&acc)[2][2][4][2], const Unit& u, int wr, int wc, int fr, int fq) const {
;     ...
;                     } else if constexpr (MODE == EP_RES) {
;                         const int c = pn * 256 + ct; EGAS bf16_t* xb = (EGAS bf16_t*)((EGAS unsigned char*)p.fo + 67108864) + row * 2048 + c; f32x4 x0, x1;
;                         if (p.f0) { const EGAS float* xi = (const EGAS float*)p.f0 + row * 2048 + c; x0 = *(const EGAS f32x4*)xi; x1 = *(const EGAS f32x4*)(xi + 4); } else ld8(xb, x0, x1);
;                         st8(xb, x0 + v0, x1 + v1);
	s_nop 0
	v_lshlrev_b32_e32 v46, 16, v208
	v_and_b32_e32 v47, 0xffff0000, v208
	v_lshlrev_b32_e32 v48, 16, v209
	v_and_b32_e32 v49, 0xffff0000, v209
	v_lshlrev_b32_e32 v50, 16, v210
	v_and_b32_e32 v51, 0xffff0000, v210
	v_lshlrev_b32_e32 v52, 16, v211
	v_and_b32_e32 v53, 0xffff0000, v211
	v_pk_add_f32 v[48:49], v[56:57], v[48:49]
	v_pk_add_f32 v[46:47], v[54:55], v[46:47]
	v_pk_add_f32 v[52:53], v[44:45], v[52:53]
	v_pk_add_f32 v[44:45], v[42:43], v[50:51]
	v_cvt_pk_bf16_f32 v42, v46, v47
	v_cvt_pk_bf16_f32 v43, v48, v49
	v_mov_b32_e32 v51, v1
	v_cvt_pk_bf16_f32 v44, v44, v45
	v_cvt_pk_bf16_f32 v45, v52, v53
	v_add_u32_e32 v50, 0x50000, v0
	v_lshl_add_u64 v[50:51], v[50:51], 1, s[8:9]
	global_store_dwordx4 v[66:67], v[42:45], off
	v_lshl_add_u64 v[50:51], v[50:51], 0, v[142:143]
	v_add_u32_e32 v0, 0x58000, v0
	s_waitcnt vmcnt(13)
	v_lshlrev_b32_e32 v42, 16, v212
	v_and_b32_e32 v43, 0xffff0000, v212
	v_lshlrev_b32_e32 v44, 16, v213
	v_and_b32_e32 v45, 0xffff0000, v213
	v_lshlrev_b32_e32 v46, 16, v214
	v_and_b32_e32 v47, 0xffff0000, v214
	v_lshlrev_b32_e32 v48, 16, v215
	v_and_b32_e32 v49, 0xffff0000, v215
	v_pk_add_f32 v[36:37], v[36:37], v[44:45]
	v_pk_add_f32 v[34:35], v[34:35], v[42:43]
	v_pk_add_f32 v[42:43], v[32:33], v[48:49]
	v_pk_add_f32 v[32:33], v[30:31], v[46:47]
	v_cvt_pk_bf16_f32 v30, v34, v35
	v_cvt_pk_bf16_f32 v31, v36, v37
	s_nop 0
	v_cvt_pk_bf16_f32 v32, v32, v33
	v_cvt_pk_bf16_f32 v33, v42, v43
	s_nop 0
	global_store_dwordx4 v[66:67], v[30:33], off offset:256
	s_waitcnt vmcnt(12)
	s_nop 0
	v_lshlrev_b32_e32 v30, 16, v216
	v_and_b32_e32 v31, 0xffff0000, v216
	v_lshlrev_b32_e32 v32, 16, v217
	v_and_b32_e32 v33, 0xffff0000, v217
	v_lshlrev_b32_e32 v34, 16, v218
	v_and_b32_e32 v35, 0xffff0000, v218
	v_lshlrev_b32_e32 v36, 16, v219
	v_and_b32_e32 v37, 0xffff0000, v219
	v_pk_add_f32 v[32:33], v[40:41], v[32:33]
	v_pk_add_f32 v[30:31], v[38:39], v[30:31]
	v_pk_add_f32 v[36:37], v[28:29], v[36:37]
	v_pk_add_f32 v[28:29], v[26:27], v[34:35]
	v_cvt_pk_bf16_f32 v26, v30, v31
	v_cvt_pk_bf16_f32 v27, v32, v33
	v_lshl_add_u64 v[34:35], v[0:1], 1, s[8:9]
	v_cvt_pk_bf16_f32 v28, v28, v29
	v_cvt_pk_bf16_f32 v29, v36, v37
	v_lshl_add_u64 v[34:35], v[34:35], 0, v[142:143]
	global_store_dwordx4 v[50:51], v[26:29], off
	s_waitcnt vmcnt(11)
	s_nop 0
	v_lshlrev_b32_e32 v26, 16, v220
	v_and_b32_e32 v27, 0xffff0000, v220
	v_lshlrev_b32_e32 v28, 16, v221
	v_and_b32_e32 v29, 0xffff0000, v221
	v_lshlrev_b32_e32 v30, 16, v222
	v_and_b32_e32 v31, 0xffff0000, v222
	v_lshlrev_b32_e32 v32, 16, v223
	v_and_b32_e32 v33, 0xffff0000, v223
	v_pk_add_f32 v[20:21], v[20:21], v[28:29]
	v_pk_add_f32 v[18:19], v[18:19], v[26:27]
	v_pk_add_f32 v[26:27], v[16:17], v[32:33]
	v_pk_add_f32 v[16:17], v[14:15], v[30:31]
	v_cvt_pk_bf16_f32 v14, v18, v19
	v_cvt_pk_bf16_f32 v15, v20, v21
	s_nop 0
	v_cvt_pk_bf16_f32 v16, v16, v17
	v_cvt_pk_bf16_f32 v17, v26, v27
	s_nop 0
	global_store_dwordx4 v[50:51], v[14:17], off offset:256
	s_waitcnt vmcnt(10)
	s_nop 0
	v_lshlrev_b32_e32 v14, 16, v224
	v_and_b32_e32 v15, 0xffff0000, v224
	v_lshlrev_b32_e32 v16, 16, v225
	v_and_b32_e32 v17, 0xffff0000, v225
	v_lshlrev_b32_e32 v18, 16, v226
	v_and_b32_e32 v19, 0xffff0000, v226
	v_lshlrev_b32_e32 v20, 16, v227
	v_and_b32_e32 v21, 0xffff0000, v227
	v_pk_add_f32 v[16:17], v[24:25], v[16:17]
	v_pk_add_f32 v[14:15], v[22:23], v[14:15]
	v_pk_add_f32 v[20:21], v[12:13], v[20:21]
	v_pk_add_f32 v[12:13], v[10:11], v[18:19]
	v_cvt_pk_bf16_f32 v10, v14, v15
	v_cvt_pk_bf16_f32 v11, v16, v17
	s_nop 0
	v_cvt_pk_bf16_f32 v12, v12, v13
	v_cvt_pk_bf16_f32 v13, v20, v21
	s_nop 0
	global_store_dwordx4 v[34:35], v[10:13], off
	s_waitcnt vmcnt(9)
	s_nop 0
	v_lshlrev_b32_e32 v10, 16, v228
	v_and_b32_e32 v11, 0xffff0000, v228
	v_lshlrev_b32_e32 v12, 16, v229
	v_and_b32_e32 v13, 0xffff0000, v229
	v_lshlrev_b32_e32 v14, 16, v230
	v_and_b32_e32 v15, 0xffff0000, v230
	v_lshlrev_b32_e32 v16, 16, v231
	v_and_b32_e32 v17, 0xffff0000, v231
	v_pk_add_f32 v[6:7], v[6:7], v[10:11]
	v_pk_add_f32 v[10:11], v[4:5], v[16:17]
	v_pk_add_f32 v[4:5], v[2:3], v[14:15]
	v_pk_add_f32 v[8:9], v[8:9], v[12:13]
	v_cvt_pk_bf16_f32 v2, v6, v7
	s_nop 0
	v_cvt_pk_bf16_f32 v3, v8, v9
	v_cvt_pk_bf16_f32 v4, v4, v5
	v_cvt_pk_bf16_f32 v5, v10, v11
	global_store_dwordx4 v[34:35], v[2:5], off offset:256
	s_cbranch_vccnz .LBB0_1907
	s_andn2_b64 vcc, exec, s[4:5]
	s_cbranch_vccnz .LBB0_1906
	s_barrier
	s_branch .LBB0_1906
